# add: attention epilogue widened to dwordx4 stores via permlane16_swap + gate prefetch; S5 pass-B recurrence in FMA form, folded gelu constant, immediate-offset store addresses
# speedup vs baseline: 1.0275x; 1.0125x over previous
; #define LAS __attribute__((address_space(3)))
; __device__ __forceinline__ unsigned cvt_pk_bf16(float lo, float hi) { unsigned r; asm volatile("v_cvt_pk_bf16_f32 %0, %1, %2" : "=v"(r) : "v"(lo), "v"(hi)); return r; }
; __device__ __forceinline__ float bflo(unsigned w) { return __uint_as_float(w << 16); }
; __device__ __forceinline__ float bfhi(unsigned w) { return __uint_as_float(w & 0xffff0000u); }
; __device__ __forceinline__ void attn_unit(LAS unsigned char* lds, const bf16_t* Qm, const bf16_t* Km, const bf16_t* VT, const bf16_t* GBm, bf16_t* YB, int b, int hp, int qb) {
;     ...
;     const int tid = tidl_, wave = tid >> 6, lane = tid & 63, fr = lane & 15, fq = lane >> 4;
;     const int hsel = wave >> 2, h = 2 * hp + hsel;
;     const int q0 = qb * 64, qw = q0 + (hsel ? 3 - (wave & 3) : (wave & 3)) * 16;
;     const size_t rowbase = (size_t)b * SEQ;
;     LAS unsigned char* KL = lds + hsel * 35840;
;     LAS unsigned char* VL = KL + 17408;
;     volatile LAS int* FL = (volatile LAS int*)(lds + 71680);
;     bf16x8 qf[4];
;     { const bf16_t* qp = Qm + (rowbase + qw + fr) * 1024 + h * 128 + fq * 8;
; #pragma unroll
;       for (int ks = 0; ks < 4; ++ks) qf[ks] = *(const bf16x8*)(qp + ks * 32); }
;     f32x4 o[8];
; #pragma unroll
;     for (int d = 0; d < 8; ++d) o[d] = (f32x4){0.f, 0.f, 0.f, 0.f};
;     float Rs = 1.f;
;     int kb = q0 >> 6;
;     u32x4 pk[4], pv[4];
;     ...
;     {
;         const size_t off = (rowbase + qw + fr) * 1024 + h * 128 + fq * 4;
; #pragma unroll
;         for (int db = 0; db < 8; ++db) {
;             const u32x2 gw = *(const u32x2*)(GBm + off + db * 16);
;             u32x2 w; w.x = cvt_pk_bf16(o[db][0] * bflo(gw.x), o[db][1] * bfhi(gw.x)); w.y = cvt_pk_bf16(o[db][2] * bflo(gw.y), o[db][3] * bfhi(gw.y));
;             *(u32x2*)(YB + off + db * 16) = w;
;         }
;     }
.LBB0_514:
	v_lshl_add_u64 v[0:1], v[82:83], 0, v[84:85]
	v_lshl_or_b32 v0, v106, 2, v0
	v_lshlrev_b64 v[0:1], 1, v[0:1]
	v_lshl_add_u64 v[0:1], s[20:21], 0, v[0:1]
	v_and_b32_e32 v2, 1, v106
	v_mul_u32_u24_e32 v2, 24, v2
	v_mov_b32_e32 v3, 0
	v_lshl_add_u64 v[0:1], v[2:3], 0, v[0:1]
	s_add_i32 s39, s39, s34
	s_cmpk_gt_i32 s39, 0x7ff
	s_waitcnt vmcnt(0)
	v_lshlrev_b32_e32 v6, 16, v172
	v_and_b32_e32 v4, 0xffff0000, v172
	v_lshlrev_b32_e32 v7, 16, v173
	v_and_b32_e32 v5, 0xffff0000, v173
	v_mul_f32_e32 v6, v60, v6
	v_mul_f32_e32 v4, v61, v4
	v_mul_f32_e32 v7, v62, v7
	v_mul_f32_e32 v5, v63, v5
	v_cvt_pk_bf16_f32 v208, v6, v4
	v_cvt_pk_bf16_f32 v209, v7, v5
	v_lshlrev_b32_e32 v10, 16, v174
	v_and_b32_e32 v8, 0xffff0000, v174
	v_lshlrev_b32_e32 v11, 16, v175
	v_and_b32_e32 v9, 0xffff0000, v175
	v_mul_f32_e32 v10, v72, v10
	v_mul_f32_e32 v8, v73, v8
	v_mul_f32_e32 v11, v74, v11
	v_mul_f32_e32 v9, v75, v9
	v_cvt_pk_bf16_f32 v210, v10, v8
	v_cvt_pk_bf16_f32 v211, v11, v9
	v_lshlrev_b32_e32 v6, 16, v176
	v_and_b32_e32 v4, 0xffff0000, v176
	v_lshlrev_b32_e32 v7, 16, v177
	v_and_b32_e32 v5, 0xffff0000, v177
	v_mul_f32_e32 v6, v56, v6
	v_mul_f32_e32 v4, v57, v4
	v_mul_f32_e32 v7, v58, v7
	v_mul_f32_e32 v5, v59, v5
	v_cvt_pk_bf16_f32 v212, v6, v4
	v_cvt_pk_bf16_f32 v213, v7, v5
	v_lshlrev_b32_e32 v10, 16, v178
	v_and_b32_e32 v8, 0xffff0000, v178
	v_lshlrev_b32_e32 v11, 16, v179
	v_and_b32_e32 v9, 0xffff0000, v179
	v_mul_f32_e32 v10, v44, v10
	v_mul_f32_e32 v8, v45, v8
	v_mul_f32_e32 v11, v46, v11
	v_mul_f32_e32 v9, v47, v9
	v_cvt_pk_bf16_f32 v214, v10, v8
	v_cvt_pk_bf16_f32 v215, v11, v9
	v_lshlrev_b32_e32 v6, 16, v180
	v_and_b32_e32 v4, 0xffff0000, v180
	v_lshlrev_b32_e32 v7, 16, v181
	v_and_b32_e32 v5, 0xffff0000, v181
	v_mul_f32_e32 v6, v32, v6
	v_mul_f32_e32 v4, v33, v4
	v_mul_f32_e32 v7, v34, v7
	v_mul_f32_e32 v5, v35, v5
	v_cvt_pk_bf16_f32 v240, v6, v4
	v_cvt_pk_bf16_f32 v241, v7, v5
	v_lshlrev_b32_e32 v10, 16, v182
	v_and_b32_e32 v8, 0xffff0000, v182
	v_lshlrev_b32_e32 v11, 16, v183
	v_and_b32_e32 v9, 0xffff0000, v183
	v_mul_f32_e32 v10, v24, v10
	v_mul_f32_e32 v8, v25, v8
	v_mul_f32_e32 v11, v26, v11
	v_mul_f32_e32 v9, v27, v9
	v_cvt_pk_bf16_f32 v242, v10, v8
	v_cvt_pk_bf16_f32 v243, v11, v9
	v_lshlrev_b32_e32 v6, 16, v184
	v_and_b32_e32 v4, 0xffff0000, v184
	v_lshlrev_b32_e32 v7, 16, v185
	v_and_b32_e32 v5, 0xffff0000, v185
	v_mul_f32_e32 v6, v20, v6
	v_mul_f32_e32 v4, v21, v4
	v_mul_f32_e32 v7, v22, v7
	v_mul_f32_e32 v5, v23, v5
	v_cvt_pk_bf16_f32 v244, v6, v4
	v_cvt_pk_bf16_f32 v245, v7, v5
	v_lshlrev_b32_e32 v10, 16, v186
	v_and_b32_e32 v8, 0xffff0000, v186
	v_lshlrev_b32_e32 v11, 16, v187
	v_and_b32_e32 v9, 0xffff0000, v187
	v_mul_f32_e32 v10, v16, v10
	v_mul_f32_e32 v8, v17, v8
	v_mul_f32_e32 v11, v18, v11
	v_mul_f32_e32 v9, v19, v9
	v_cvt_pk_bf16_f32 v246, v10, v8
	v_cvt_pk_bf16_f32 v247, v11, v9
	s_nop 1
	v_permlane16_swap_b32_e32 v208, v210
	v_permlane16_swap_b32_e32 v209, v211
	v_permlane16_swap_b32_e32 v212, v214
	v_permlane16_swap_b32_e32 v213, v215
	v_permlane16_swap_b32_e32 v240, v242
	v_permlane16_swap_b32_e32 v241, v243
	v_permlane16_swap_b32_e32 v244, v246
	v_permlane16_swap_b32_e32 v245, v247
	global_store_dwordx4 v[0:1], v[208:211], off
	global_store_dwordx4 v[0:1], v[212:215], off offset:64
	global_store_dwordx4 v[0:1], v[240:243], off offset:128
	global_store_dwordx4 v[0:1], v[244:247], off offset:192
	s_barrier
	s_cbranch_scc1 .LBB0_524
.LBB0_515:
	v_mov_b32_e32 v32, v226
	s_ashr_i32 s0, s39, 4
	s_sub_i32 s0, 0x7f, s0
	v_ashrrev_i32_e32 v33, 6, v32
	v_bitop3_b32 v0, v33, 3, v33 bitop3:0xc
	v_cmp_gt_u32_e32 vcc, s6, v32
	s_lshl_b32 s1, s39, 11
	s_lshl_b32 s56, s0, 6
	v_cndmask_b32_e32 v0, v0, v33, vcc
	s_and_b32 s60, s1, 0x6000
	s_lshl_b32 s1, s39, 8
	v_lshl_add_u32 v44, v0, 4, s56
	s_and_b32 s8, s1, 0x300
	s_and_b32 s61, s0, 0x3ffffff
	s_add_i32 s9, s56, s60
	s_lshl_b32 s0, s60, 1
	v_and_b32_e32 v34, 15, v32
	v_add_u32_e32 v0, s60, v44
	s_add_u32 s0, s26, s0
	v_bitop3_b32 v36, v32, s7, v104 bitop3:0x6c
	v_ashrrev_i32_e32 v35, 8, v32
	v_or_b32_e32 v80, v0, v34
	s_addc_u32 s1, s27, 0
	s_lshl_b64 s[4:5], s[56:57], 1
	v_lshrrev_b32_e32 v88, 4, v36
	v_lshlrev_b64 v[0:1], 11, v[80:81]
	v_lshl_add_u32 v84, v35, 7, s8
	s_add_u32 s4, s0, s4
	v_lshlrev_b32_e32 v22, 4, v32
	v_bfe_u32 v86, v32, 4, 6
	v_bfe_u32 v45, v32, 3, 7
	v_or_b32_e32 v26, s9, v88
	v_mov_b32_e32 v27, v81
	v_lshl_add_u64 v[0:1], s[46:47], 0, v[0:1]
	v_ashrrev_i32_e32 v85, 31, v84
	s_addc_u32 s5, s1, s5
	v_and_b32_e32 v16, 0x70, v22
	v_mov_b32_e32 v17, v81
	v_or_b32_e32 v20, s9, v86
	v_mov_b32_e32 v21, v81
	v_or_b32_e32 v46, s8, v45
	v_lshlrev_b64 v[26:27], 11, v[26:27]
	v_lshlrev_b64 v[82:83], 10, v[80:81]
	v_lshl_add_u64 v[0:1], v[84:85], 1, v[0:1]
	v_and_b32_e32 v80, 48, v32
	v_lshl_add_u64 v[18:19], s[4:5], 0, v[16:17]
	v_lshlrev_b64 v[20:21], 11, v[20:21]
	s_lshl_b32 s12, s8, 1
	s_mov_b32 s13, s57
	v_lshlrev_b32_e32 v24, 16, v46
	v_mov_b32_e32 v25, v81
	v_lshl_add_u64 v[26:27], s[44:45], 0, v[26:27]
	v_lshrrev_b32_e32 v47, 3, v36
	v_lshl_add_u64 v[12:13], v[0:1], 0, v[80:81]
	v_lshl_add_u64 v[20:21], s[44:45], 0, v[20:21]
	v_and_b32_e32 v22, 0xf0, v22
	v_mov_b32_e32 v23, v81
	v_lshl_add_u64 v[24:25], v[18:19], 0, v[24:25]
	v_lshl_add_u64 v[26:27], v[26:27], 0, s[12:13]
	v_or_b32_e32 v56, s8, v47
; #define ATT_LOAD(kbi) do { const int k0_ = (kbi) * 64; _Pragma("unroll") for (int i_ = 0; i_ < 4; ++i_) { const int ci = (tid + 512 * i_) & 1023, hh_ = 2 * hp + (i_ >> 1); \
;         pk[i_] = *(const u32x4*)(Km + (rowbase + k0_ + (ci >> 4)) * 1024 + hh_ * 128 + (ci & 15) * 8); \
;         pv[i_] = *(const u32x4*)(VT + (size_t)(hh_ * 128 + (ci >> 3)) * T + rowbase + k0_ + (ci & 7) * 8); } } while (0)
; __device__ __forceinline__ void attn_unit(LAS unsigned char* lds, const bf16_t* Qm, const bf16_t* Km, const bf16_t* VT, const bf16_t* GBm, bf16_t* YB, int b, int hp, int qb) {
;     ...
;     { const bf16_t* qp = Qm + (rowbase + qw + fr) * 1024 + h * 128 + fq * 8;
; #pragma unroll
;       for (int ks = 0; ks < 4; ++ks) qf[ks] = *(const bf16x8*)(qp + ks * 32); }
;     f32x4 o[8];
; #pragma unroll
;     for (int d = 0; d < 8; ++d) o[d] = (f32x4){0.f, 0.f, 0.f, 0.f};
;     float Rs = 1.f;
;     int kb = q0 >> 6;
;     u32x4 pk[4], pv[4];
;     ...
;     ATT_LOAD(kb);
;     ...
;     {
;         const size_t off = (rowbase + qw + fr) * 1024 + h * 128 + fq * 4;
; #pragma unroll
;         for (int db = 0; db < 8; ++db) {
;             const u32x2 gw = *(const u32x2*)(GBm + off + db * 16);
	v_lshl_add_u64 v[188:189], v[82:83], 0, v[84:85]
	v_bfe_u32 v190, v226, 4, 2
	v_lshl_or_b32 v188, v190, 2, v188
	v_lshlrev_b64 v[188:189], 1, v[188:189]
	v_lshl_add_u64 v[188:189], s[30:31], 0, v[188:189]
	global_load_dwordx2 v[172:173], v[188:189], off
	global_load_dwordx2 v[174:175], v[188:189], off offset:32
	global_load_dwordx2 v[176:177], v[188:189], off offset:64
	global_load_dwordx2 v[178:179], v[188:189], off offset:96
	global_load_dwordx2 v[180:181], v[188:189], off offset:128
	global_load_dwordx2 v[182:183], v[188:189], off offset:160
	global_load_dwordx2 v[184:185], v[188:189], off offset:192
	global_load_dwordx2 v[186:187], v[188:189], off offset:224
	global_load_dwordx4 v[0:3], v[12:13], off
	global_load_dwordx4 v[4:7], v[12:13], off offset:64
	global_load_dwordx4 v[8:11], v[12:13], off offset:128
	s_nop 0
	global_load_dwordx4 v[12:15], v[12:13], off offset:192
	v_lshl_add_u64 v[20:21], v[20:21], 0, s[12:13]
	v_lshl_add_u64 v[26:27], v[26:27], 0, v[22:23]
	v_lshrrev_b32_e32 v196, 3, v226
	v_and_b32_e32 v197, 7, v226
	v_lshlrev_b32_e32 v197, 4, v197
	v_add_u32_e32 v198, s8, v196
	v_lshlrev_b32_e32 v198, 16, v198
	v_or_b32_e32 v198, v198, v197
	v_mov_b32_e32 v199, 0
	s_mov_b32 s66, 0x400000
	s_mov_b32 s67, 0
	v_lshl_add_u64 v[216:217], v[198:199], 0, s[26:27]
	v_lshl_add_u64 v[218:219], v[216:217], 0, s[66:67]
	v_lshl_add_u64 v[220:221], v[218:219], 0, s[66:67]
	v_lshl_add_u64 v[222:223], v[220:221], 0, s[66:67]
	v_lshlrev_b32_e32 v196, 7, v196
	v_add_u32_e32 v228, 0x2000, v196
	v_add_u32_e32 v229, 0x4000, v196
	v_add_u32_e32 v230, 0x6000, v196
	v_mov_b32_e32 v233, 0
	v_mov_b32_e32 v235, 0
	v_mov_b32_e32 v237, 0
	v_mov_b32_e32 v239, 0
	s_add_i32 s68, s60, s56
	s_lshl_b32 s68, s68, 1
	v_xor_b32_e32 v232, s68, v196
	v_xor_b32_e32 v234, s68, v228
	v_xor_b32_e32 v236, s68, v229
	v_xor_b32_e32 v238, s68, v230
	v_lshl_add_u64 v[200:201], v[232:233], 0, v[216:217]
	v_lshl_add_u64 v[202:203], v[234:235], 0, v[218:219]
	v_lshl_add_u64 v[204:205], v[236:237], 0, v[220:221]
	v_lshl_add_u64 v[206:207], v[238:239], 0, v[222:223]
	global_load_dwordx4 v[28:31], v[200:201], off
	global_load_dwordx4 v[40:43], v[26:27], off
	v_lshlrev_b32_e32 v24, 16, v56
	v_mov_b32_e32 v25, v81
	s_or_b32 s58, s8, 0x80
	v_lshl_add_u64 v[20:21], v[20:21], 0, v[22:23]
	v_lshl_add_u64 v[24:25], v[18:19], 0, v[24:25]
	v_or_b32_e32 v57, s58, v45
	global_load_dwordx4 v[36:39], v[20:21], off
	global_load_dwordx4 v[48:51], v[20:21], off offset:256
	v_lshlrev_b32_e32 v20, 16, v57
	v_mov_b32_e32 v21, v81
	global_load_dwordx4 v[52:55], v[202:203], off
	global_load_dwordx4 v[64:67], v[26:27], off offset:256
	v_or_b32_e32 v26, s58, v47
	v_lshl_add_u64 v[20:21], v[18:19], 0, v[20:21]
	v_lshlrev_b32_e32 v24, 16, v26
	v_mov_b32_e32 v25, v81
	v_lshl_add_u64 v[18:19], v[18:19], 0, v[24:25]
	global_load_dwordx4 v[68:71], v[204:205], off
	global_load_dwordx4 v[76:79], v[206:207], off
	v_lshl_add_u64 v[90:91], s[0:1], 0, v[16:17]
	v_lshlrev_b32_e32 v17, 1, v32
	v_and_b32_e32 v21, 3, v32
	v_and_or_b32 v17, v17, 24, v21
	v_add_u32_e32 v21, 16, v32
	v_mul_i32_i24_e32 v19, 0x8c00, v35
	v_and_b32_e32 v21, 63, v21
	v_add_u32_e32 v25, 48, v32
	v_mad_u32_u24 v35, v45, s38, 0
	v_mad_u32_u24 v45, v47, s38, 0
	s_add_u32 s12, s44, s12
	v_and_b32_e32 v25, 63, v25
	s_addc_u32 s13, s45, 0
	v_add_u32_e32 v113, v35, v16
	v_add_u32_e32 v115, v45, v16
	v_or_b32_e32 v16, v105, v21
	v_and_b32_e32 v107, 63, v32
	v_bfe_u32 v106, v32, 4, 2
	v_lshlrev_b32_e32 v18, 15, v46
	v_lshlrev_b32_e32 v20, 15, v56
	v_lshlrev_b32_e32 v24, 15, v57
	v_lshlrev_b32_e32 v26, 15, v26
	v_or_b32_e32 v109, 15, v44
	v_lshl_add_u32 v110, v33, 2, s28
	v_add3_u32 v19, 0, v19, v80
	v_or_b32_e32 v111, v44, v34
	v_mad_u32_u24 v27, v86, s29, 0
	v_mad_u32_u24 v44, v88, s29, 0
	v_lshl_add_u64 v[92:93], s[12:13], 0, v[22:23]
	v_lshl_add_u64 v[32:33], s[44:45], 0, v[22:23]
	v_mul_u32_u24_e32 v17, 0x110, v17
	v_mul_u32_u24_e32 v23, 0x90, v34
	s_lshl_b32 s12, s58, 1
	s_mov_b32 s13, s57
	v_mov_b32_e32 v60, v81
	v_mov_b32_e32 v61, v81
	v_mov_b32_e32 v62, v81
	v_mov_b32_e32 v63, v81
	v_lshlrev_b32_e32 v118, 2, v16
	v_or_b32_e32 v16, v105, v25
	v_lshl_add_u64 v[94:95], v[32:33], 0, s[12:13]
	v_add_u32_e32 v112, v27, v22
	v_add_u32_e32 v114, v44, v22
	v_lshlrev_b32_e32 v80, 1, v18
	v_lshlrev_b32_e32 v98, 1, v20
	v_lshlrev_b32_e32 v100, 1, v24
	v_lshlrev_b32_e32 v102, 1, v26
	v_add_u32_e32 v116, v19, v17
	v_add_u32_e32 v117, v19, v23
	v_lshlrev_b32_e32 v119, 2, v16
	v_mov_b64_e32 v[74:75], v[62:63]
	v_mov_b64_e32 v[56:57], v[60:61]
	v_mov_b64_e32 v[44:45], v[60:61]
	v_mov_b64_e32 v[32:33], v[60:61]
	v_mov_b64_e32 v[24:25], v[60:61]
	v_mov_b64_e32 v[20:21], v[60:61]
	v_mov_b64_e32 v[16:17], v[60:61]
	v_lshlrev_b32_e32 v108, 3, v106
	v_mov_b32_e32 v87, v81
	v_mov_b32_e32 v89, v81
	v_cmp_eq_u32_e64 s[0:1], 3, v106
	v_cmp_gt_u32_e64 s[10:11], 32, v107
	v_cmp_gt_u32_e64 s[4:5], 16, v107
	v_cmp_eq_u32_e64 s[8:9], 0, v107
	s_lshl_b32 s62, s61, 3
	s_sub_i32 s56, s56, 64
	v_mov_b32_e32 v96, 1.0
	s_mov_b32 s63, s57
	v_mov_b64_e32 v[72:73], v[60:61]
	v_mov_b64_e32 v[58:59], v[62:63]
	v_mov_b64_e32 v[46:47], v[62:63]
	v_mov_b64_e32 v[34:35], v[62:63]
	v_mov_b64_e32 v[26:27], v[62:63]
	v_mov_b64_e32 v[22:23], v[62:63]
	v_mov_b64_e32 v[18:19], v[62:63]
	s_branch .LBB0_517

; #define LAS __attribute__((address_space(3)))
; __device__ __forceinline__ unsigned cvt_pk_bf16(float lo, float hi) { unsigned r; asm volatile("v_cvt_pk_bf16_f32 %0, %1, %2" : "=v"(r) : "v"(lo), "v"(hi)); return r; }
; #define LDS_WAIT() asm volatile("s_waitcnt lgkmcnt(0)" ::: "memory")
; template <bool PASSB>
; __device__ __forceinline__ void s5_phase(LAS unsigned char* lds, const Params& p) {
;     ...
; #pragma unroll
;             for (int nb = 0; nb < 8; ++nb) {
;                 const f32x4 d = __builtin_amdgcn_mfma_f32_16x16x32_bf16(au, bfm[nb], (f32x4){0.f, 0.f, 0.f, 0.f}, 0, 0, 0);
;                 *(LAS f32x4*)(BuL + (nb * 16 + fr) * 20 + fq * 4) = d;
;             }
;             LDS_WAIT();
;             f32x4 br4[4], bi4[4];
; #pragma unroll
;             for (int q = 0; q < 4; ++q) { br4[q] = *(const LAS f32x4*)(BuL + lane * 20 + q * 4); bi4[q] = *(const LAS f32x4*)(BuL + (64 + lane) * 20 + q * 4); }
; #pragma unroll
;             for (int t = 0; t < 16; ++t) {
;                 const float bur = br4[t >> 2][t & 3], bui = bi4[t >> 2][t & 3];
;                 const float nr = are * hr - aim * hi + bur, ni = are * hi + aim * hr + bui; hr = nr; hi = ni;
;                 if (PASSB) *(LAS unsigned*)(HbL + t * 272 + lane * 4) = cvt_pk_bf16(hr, hi);
;             }
.LBB0_1093:
	s_or_b64 exec, exec, s[24:25]
	v_mfma_f32_16x16x32_bf16 v[112:115], v[68:71], v[8:11], 0
	v_mfma_f32_16x16x32_bf16 v[116:119], v[68:71], v[4:7], 0
	s_nop 6
	ds_write_b128 v107, v[112:115]
	s_add_i32 s23, s23, 1
	v_mfma_f32_16x16x32_bf16 v[120:123], v[68:71], v[16:19], 0
	v_lshl_add_u64 v[98:99], v[98:99], 0, s[64:65]
	s_cmp_eq_u32 s23, 32
	v_mfma_f32_16x16x32_bf16 v[124:127], v[68:71], v[12:15], 0
	ds_write_b128 v107, v[116:119] offset:1280
	s_nop 3
	ds_write_b128 v107, v[120:123] offset:2560
	s_nop 1
	ds_write_b128 v107, v[124:127] offset:3840
	v_mfma_f32_16x16x32_bf16 v[128:131], v[68:71], v[20:23], 0
	v_mfma_f32_16x16x32_bf16 v[112:115], v[68:71], v[24:27], 0
	v_mfma_f32_16x16x32_bf16 v[116:119], v[68:71], v[28:31], 0
	s_nop 5
	ds_write_b128 v107, v[128:131] offset:5120
	ds_write_b128 v107, v[112:115] offset:6400
	ds_write_b128 v107, v[116:119] offset:7680
	v_mfma_f32_16x16x32_bf16 v[112:115], v[68:71], v[32:35], 0
	v_mfma_f32_16x16x32_bf16 v[68:71], v[68:71], v[52:55], 0
	s_nop 6
	ds_write_b128 v107, v[112:115] offset:8960
	s_waitcnt lgkmcnt(0)
	ds_read_b128 v[112:115], v108
	ds_read_b128 v[116:119], v108 offset:16
	ds_read_b128 v[120:123], v108 offset:32
	ds_read_b128 v[124:127], v108 offset:48
	ds_read_b128 v[128:131], v108 offset:5120
	ds_read_b128 v[132:135], v108 offset:5136
	ds_read_b128 v[136:139], v108 offset:5152
	ds_read_b128 v[140:143], v108 offset:5168
	s_waitcnt lgkmcnt(3)
	v_fmac_f32_e32 v112, v88, v94
	v_fmac_f32_e32 v128, v88, v95
	v_fma_f32 v112, -v92, v95, v112
	v_fmac_f32_e32 v128, v92, v94
	v_cvt_pk_bf16_f32 v1, v112, v128
	ds_write_b32 v109, v1 offset:10240
	v_fmac_f32_e32 v113, v88, v112
	v_fmac_f32_e32 v129, v88, v128
	v_fma_f32 v113, -v92, v128, v113
	v_fmac_f32_e32 v129, v92, v112
	v_cvt_pk_bf16_f32 v152, v113, v129
	ds_write_b32 v109, v152 offset:10512
	v_fmac_f32_e32 v114, v88, v113
	v_fmac_f32_e32 v130, v88, v129
	v_fma_f32 v114, -v92, v129, v114
	v_fmac_f32_e32 v130, v92, v113
	v_cvt_pk_bf16_f32 v1, v114, v130
	ds_write_b32 v109, v1 offset:10784
	v_fmac_f32_e32 v115, v88, v114
	v_fmac_f32_e32 v131, v88, v130
	v_fma_f32 v115, -v92, v130, v115
	v_fmac_f32_e32 v131, v92, v114
	v_cvt_pk_bf16_f32 v152, v115, v131
	ds_write_b32 v109, v152 offset:11056
	s_waitcnt lgkmcnt(6)
	v_fmac_f32_e32 v116, v88, v115
	v_fmac_f32_e32 v132, v88, v131
	v_fma_f32 v116, -v92, v131, v116
	v_fmac_f32_e32 v132, v92, v115
	v_cvt_pk_bf16_f32 v1, v116, v132
	ds_write_b32 v109, v1 offset:11328
	v_fmac_f32_e32 v117, v88, v116
	v_fmac_f32_e32 v133, v88, v132
	v_fma_f32 v117, -v92, v132, v117
	v_fmac_f32_e32 v133, v92, v116
	v_cvt_pk_bf16_f32 v152, v117, v133
	ds_write_b32 v109, v152 offset:11600
	v_fmac_f32_e32 v118, v88, v117
	v_fmac_f32_e32 v134, v88, v133
	v_fma_f32 v118, -v92, v133, v118
	v_fmac_f32_e32 v134, v92, v117
	v_cvt_pk_bf16_f32 v1, v118, v134
	ds_write_b32 v109, v1 offset:11872
	v_fmac_f32_e32 v119, v88, v118
	v_fmac_f32_e32 v135, v88, v134
	v_fma_f32 v119, -v92, v134, v119
	v_fmac_f32_e32 v135, v92, v118
	v_cvt_pk_bf16_f32 v152, v119, v135
	ds_write_b32 v109, v152 offset:12144
	s_waitcnt lgkmcnt(9)
	v_fmac_f32_e32 v120, v88, v119
	v_fmac_f32_e32 v136, v88, v135
	v_fma_f32 v120, -v92, v135, v120
	v_fmac_f32_e32 v136, v92, v119
	v_cvt_pk_bf16_f32 v1, v120, v136
	ds_write_b32 v109, v1 offset:12416
	v_fmac_f32_e32 v121, v88, v120
	v_fmac_f32_e32 v137, v88, v136
	v_fma_f32 v121, -v92, v136, v121
	v_fmac_f32_e32 v137, v92, v120
	v_cvt_pk_bf16_f32 v152, v121, v137
	ds_write_b32 v109, v152 offset:12688
	v_fmac_f32_e32 v122, v88, v121
	v_fmac_f32_e32 v138, v88, v137
	v_fma_f32 v122, -v92, v137, v122
	v_fmac_f32_e32 v138, v92, v121
	v_cvt_pk_bf16_f32 v1, v122, v138
	ds_write_b32 v109, v1 offset:12960
	v_fmac_f32_e32 v123, v88, v122
	v_fmac_f32_e32 v139, v88, v138
	v_fma_f32 v123, -v92, v138, v123
	v_fmac_f32_e32 v139, v92, v122
	v_cvt_pk_bf16_f32 v152, v123, v139
	ds_write_b32 v109, v152 offset:13232
	s_waitcnt lgkmcnt(12)
; #define LAS __attribute__((address_space(3)))
; __device__ __forceinline__ unsigned cvt_pk_bf16(float lo, float hi) { unsigned r; asm volatile("v_cvt_pk_bf16_f32 %0, %1, %2" : "=v"(r) : "v"(lo), "v"(hi)); return r; }
; __device__ __forceinline__ float sigmoidf_(float x) { return __builtin_amdgcn_rcpf(1.0f + __expf(-x)); }
; #define LDS_WAIT() asm volatile("s_waitcnt lgkmcnt(0)" ::: "memory")
; template <bool PASSB>
; __device__ __forceinline__ void s5_phase(LAS unsigned char* lds, const Params& p) {
;     ...
;             f32x4 br4[4], bi4[4];
; #pragma unroll
;             for (int q = 0; q < 4; ++q) { br4[q] = *(const LAS f32x4*)(BuL + lane * 20 + q * 4); bi4[q] = *(const LAS f32x4*)(BuL + (64 + lane) * 20 + q * 4); }
; #pragma unroll
;             for (int t = 0; t < 16; ++t) {
;                 const float bur = br4[t >> 2][t & 3], bui = bi4[t >> 2][t & 3];
;                 const float nr = are * hr - aim * hi + bur, ni = are * hi + aim * hr + bui; hr = nr; hi = ni;
;                 if (PASSB) *(LAS unsigned*)(HbL + t * 272 + lane * 4) = cvt_pk_bf16(hr, hi);
;             }
;             if (PASSB) {
;                 LDS_WAIT();
;                 f32x4 y = __builtin_amdgcn_mfma_f32_16x16x32_bf16(au, dfm, (f32x4){0.f, 0.f, 0.f, 0.f}, 0, 0, 0);
; #pragma unroll
;                 for (int ks = 0; ks < 4; ++ks) {
;                     const bf16x8 a = *(const LAS bf16x8*)(HbL + fr * 272 + (ks * 32 + fq * 8) * 2);
;                     y = __builtin_amdgcn_mfma_f32_16x16x32_bf16(a, cfm[ks], y, 0, 0, 0);
;                 }
; #pragma unroll
;                 for (int j = 0; j < 4; ++j) {
;                     const float v = y[j];
;                     const float ge = v * sigmoidf_(1.5957691216057308f * (v + 0.044715f * v * v * v));
;                     YG[(r0 + fq * 4 + j) * 1024 + g * 16 + fr] = (bf16_t)(cvt_pk_bf16(ge, ge) & 0xffffu);
;                 }
;             }
	v_fmac_f32_e32 v124, v88, v123
	v_fmac_f32_e32 v140, v88, v139
	v_fma_f32 v124, -v92, v139, v124
	v_fmac_f32_e32 v140, v92, v123
	v_cvt_pk_bf16_f32 v1, v124, v140
	ds_write_b32 v109, v1 offset:13504
	v_fmac_f32_e32 v125, v88, v124
	v_fmac_f32_e32 v141, v88, v140
	v_fma_f32 v125, -v92, v140, v125
	v_fmac_f32_e32 v141, v92, v124
	v_cvt_pk_bf16_f32 v152, v125, v141
	ds_write_b32 v109, v152 offset:13776
	v_fmac_f32_e32 v126, v88, v125
	v_fmac_f32_e32 v142, v88, v141
	v_fma_f32 v126, -v92, v141, v126
	v_fmac_f32_e32 v142, v92, v125
	v_cvt_pk_bf16_f32 v1, v126, v142
	ds_write_b32 v109, v1 offset:14048
	v_fmac_f32_e32 v127, v88, v126
	v_fmac_f32_e32 v143, v88, v142
	v_fma_f32 v127, -v92, v142, v127
	v_fmac_f32_e32 v143, v92, v126
	v_cvt_pk_bf16_f32 v152, v127, v143
	ds_write_b32 v109, v152 offset:14320
	v_mov_b32_e32 v94, v127
	v_mov_b32_e32 v95, v143
	s_waitcnt lgkmcnt(0)
	ds_read_b128 v[112:115], v110 offset:10240
	ds_read_b128 v[116:119], v110 offset:10304
	s_waitcnt lgkmcnt(1)
	v_mfma_f32_16x16x32_bf16 v[68:71], v[112:115], v[36:39], v[68:71]
	ds_read_b128 v[112:115], v110 offset:10368
	s_waitcnt lgkmcnt(1)
	v_mfma_f32_16x16x32_bf16 v[68:71], v[116:119], v[40:43], v[68:71]
	ds_read_b128 v[116:119], v110 offset:10432
	s_waitcnt lgkmcnt(1)
	v_mfma_f32_16x16x32_bf16 v[68:71], v[112:115], v[44:47], v[68:71]
	v_or_b32_e32 v145, v97, v101
	v_or_b32_e32 v144, v96, v100
	v_lshlrev_b64 v[144:145], 11, v[144:145]
	s_mov_b64 s[80:81], 0x1000
	s_waitcnt lgkmcnt(0)
	v_mfma_f32_16x16x32_bf16 v[68:71], v[116:119], v[48:51], v[68:71]
	v_lshl_add_u64 v[144:145], v[2:3], 0, v[144:145]
	v_lshl_add_u64 v[146:147], v[144:145], 0, s[80:81]
	s_nop 5
	v_mul_f32_e32 v148, 0x3d372713, v68
	v_mul_f32_e32 v149, 0x3d372713, v69
	v_mul_f32_e32 v150, 0x3d372713, v70
	v_mul_f32_e32 v151, 0x3d372713, v71
	v_mul_f32_e32 v148, v68, v148
	v_mul_f32_e32 v149, v69, v149
	v_mul_f32_e32 v150, v70, v150
	v_mul_f32_e32 v151, v71, v151
	v_fma_f32 v148, v68, v148, v68
	v_fma_f32 v149, v69, v149, v69
	v_fma_f32 v150, v70, v150, v70
	v_fma_f32 v151, v71, v151, v71
	v_mul_f32_e32 v148, 0xc0135761, v148
	v_mul_f32_e32 v149, 0xc0135761, v149
	v_mul_f32_e32 v150, 0xc0135761, v150
	v_mul_f32_e32 v151, 0xc0135761, v151
	v_exp_f32_e32 v148, v148
	v_exp_f32_e32 v149, v149
	v_exp_f32_e32 v150, v150
	v_exp_f32_e32 v151, v151
	v_add_f32_e32 v148, 1.0, v148
	v_add_f32_e32 v149, 1.0, v149
	v_add_f32_e32 v150, 1.0, v150
	v_add_f32_e32 v151, 1.0, v151
	v_rcp_f32_e32 v148, v148
	v_rcp_f32_e32 v149, v149
	v_rcp_f32_e32 v150, v150
	v_rcp_f32_e32 v151, v151
	v_mul_f32_e32 v148, v68, v148
	v_mul_f32_e32 v149, v69, v149
	v_mul_f32_e32 v150, v70, v150
	v_mul_f32_e32 v151, v71, v151
	v_cvt_pk_bf16_f32 v148, v148, v148
	v_cvt_pk_bf16_f32 v149, v149, v149
	v_cvt_pk_bf16_f32 v150, v150, v150
	v_cvt_pk_bf16_f32 v151, v151, v151
	global_store_short v[144:145], v148, off
	global_store_short v[144:145], v149, off offset:2048
	global_store_short v[146:147], v150, off
	global_store_short v[146:147], v151, off offset:2048
	s_waitcnt lgkmcnt(0)
	v_mov_b64_e32 v[70:71], v[66:67]
	v_lshl_add_u64 v[100:101], v[100:101], 0, 16
	v_mov_b64_e32 v[68:69], v[64:65]
	s_cbranch_scc1 .LBB0_1061
